# SwiGLU epilogue stores H non-temporal so the f32 residual stream stays cache-resident for the down-projection epilogue
# baseline (speedup 1.0000x reference)
.LBB0_140:
	v_mul_f32_e32 v143, 0xbfb8aa3b, v124
	v_exp_f32_e32 v143, v143
	v_lshl_or_b32 v144, s84, 7, v140
	v_lshl_add_u32 v142, s85, 8, v138
	v_ashrrev_i32_e32 v145, 31, v144
	v_add_f32_e32 v143, 1.0, v143
	v_rcp_f32_e32 v143, v143
	s_mov_b64 s[28:29], -1
	s_and_b64 vcc, exec, s[40:41]
	v_mul_f32_e32 v124, v124, v143
	v_mul_f32_e32 v120, v120, v124
	v_mul_f32_e32 v124, 0xbfb8aa3b, v125
	v_exp_f32_e32 v124, v124
	s_nop 0
	v_add_f32_e32 v124, 1.0, v124
	v_rcp_f32_e32 v124, v124
	s_nop 0
	v_mul_f32_e32 v124, v125, v124
	v_mul_f32_e32 v121, v121, v124
	v_mul_f32_e32 v124, 0xbfb8aa3b, v126
	v_exp_f32_e32 v124, v124
	s_nop 0
	v_add_f32_e32 v124, 1.0, v124
	v_rcp_f32_e32 v124, v124
	s_nop 0
	v_mul_f32_e32 v124, v126, v124
	v_mul_f32_e32 v122, v122, v124
	v_mul_f32_e32 v124, 0xbfb8aa3b, v127
	v_exp_f32_e32 v124, v124
	s_nop 0
	v_add_f32_e32 v124, 1.0, v124
	v_rcp_f32_e32 v124, v124
	s_nop 0
	v_mul_f32_e32 v124, v127, v124
	v_mul_f32_e32 v123, v123, v124
	v_mul_f32_e32 v124, 0xbfb8aa3b, v116
	v_exp_f32_e32 v124, v124
	s_nop 0
	v_add_f32_e32 v124, 1.0, v124
	v_rcp_f32_e32 v124, v124
	s_nop 0
	v_mul_f32_e32 v116, v116, v124
	v_mul_f32_e32 v112, v112, v116
	v_mul_f32_e32 v116, 0xbfb8aa3b, v117
	v_exp_f32_e32 v116, v116
	s_nop 0
	v_add_f32_e32 v116, 1.0, v116
	v_rcp_f32_e32 v116, v116
	s_nop 0
	v_mul_f32_e32 v116, v117, v116
	v_mul_f32_e32 v113, v113, v116
	v_mul_f32_e32 v116, 0xbfb8aa3b, v118
	v_exp_f32_e32 v116, v116
	v_cvt_pk_bf16_f32 v117, v122, v123
	s_nop 0
	v_add_f32_e32 v116, 1.0, v116
	v_rcp_f32_e32 v116, v116
	s_nop 0
	v_mul_f32_e32 v116, v118, v116
	v_mul_f32_e32 v114, v114, v116
	v_mul_f32_e32 v116, 0xbfb8aa3b, v119
	v_exp_f32_e32 v116, v116
	v_cvt_pk_bf16_f32 v118, v112, v113
	v_mov_b64_e32 v[112:113], s[6:7]
	v_add_f32_e32 v116, 1.0, v116
	v_rcp_f32_e32 v116, v116
	s_nop 0
	v_mul_f32_e32 v116, v119, v116
	v_mul_f32_e32 v115, v115, v116
	v_cvt_pk_bf16_f32 v116, v120, v121
	v_cvt_pk_bf16_f32 v119, v114, v115
	v_mad_i64_i32 v[120:121], s[12:13], v142, s92, v[112:113]
	v_lshlrev_b64 v[114:115], 1, v[144:145]
	v_lshl_add_u64 v[120:121], v[120:121], 0, v[114:115]
	global_store_dwordx4 v[120:121], v[116:119], off nt
	s_nop 1
	v_mul_f32_e32 v116, 0xbfb8aa3b, v108
	v_exp_f32_e32 v116, v116
	s_nop 0
	v_add_f32_e32 v116, 1.0, v116
	v_rcp_f32_e32 v116, v116
	s_nop 0
	v_mul_f32_e32 v108, v108, v116
	v_mul_f32_e32 v104, v104, v108
	v_mul_f32_e32 v108, 0xbfb8aa3b, v109
	v_exp_f32_e32 v108, v108
	s_nop 0
	v_add_f32_e32 v108, 1.0, v108
	v_rcp_f32_e32 v108, v108
	s_nop 0
	v_mul_f32_e32 v108, v109, v108
	v_mul_f32_e32 v105, v105, v108
	v_mul_f32_e32 v108, 0xbfb8aa3b, v110
	v_exp_f32_e32 v108, v108
	s_nop 0
	v_add_f32_e32 v108, 1.0, v108
	v_rcp_f32_e32 v108, v108
	s_nop 0
	v_mul_f32_e32 v108, v110, v108
	v_mul_f32_e32 v106, v106, v108
	v_mul_f32_e32 v108, 0xbfb8aa3b, v111
	v_exp_f32_e32 v108, v108
	s_nop 0
	v_add_f32_e32 v108, 1.0, v108
	v_rcp_f32_e32 v108, v108
	s_nop 0
	v_mul_f32_e32 v108, v111, v108
	v_mul_f32_e32 v107, v107, v108
	v_mul_f32_e32 v108, 0xbfb8aa3b, v100
	v_exp_f32_e32 v108, v108
	s_nop 0
	v_add_f32_e32 v108, 1.0, v108
	v_rcp_f32_e32 v108, v108
	s_nop 0
	v_mul_f32_e32 v100, v100, v108
	v_mul_f32_e32 v100, v96, v100
	v_mul_f32_e32 v96, 0xbfb8aa3b, v101
	v_exp_f32_e32 v96, v96
	s_nop 0
	v_add_f32_e32 v96, 1.0, v96
	v_rcp_f32_e32 v96, v96
	s_nop 0
	v_mul_f32_e32 v96, v101, v96
	v_mul_f32_e32 v101, v97, v96
	v_mul_f32_e32 v96, 0xbfb8aa3b, v102
	v_exp_f32_e32 v96, v96
	v_cvt_pk_bf16_f32 v97, v106, v107
	s_nop 0
	v_add_f32_e32 v96, 1.0, v96
	v_rcp_f32_e32 v96, v96
	s_nop 0
	v_mul_f32_e32 v96, v102, v96
	v_mul_f32_e32 v102, v98, v96
	v_mul_f32_e32 v96, 0xbfb8aa3b, v103
	v_exp_f32_e32 v96, v96
	v_cvt_pk_bf16_f32 v98, v100, v101
	s_nop 0
	v_add_f32_e32 v96, 1.0, v96
	v_rcp_f32_e32 v96, v96
	s_nop 0
	v_mul_f32_e32 v96, v103, v96
	v_or_b32_e32 v103, 16, v142
	v_mad_i64_i32 v[100:101], s[12:13], v103, s92, v[112:113]
	v_mul_f32_e32 v99, v99, v96
	v_cvt_pk_bf16_f32 v96, v104, v105
	v_lshl_add_u64 v[100:101], v[100:101], 0, v[114:115]
	v_cvt_pk_bf16_f32 v99, v102, v99
	global_store_dwordx4 v[100:101], v[96:99], off nt
	s_nop 1
	v_mul_f32_e32 v96, 0xbfb8aa3b, v92
	v_exp_f32_e32 v96, v96
	s_nop 0
	v_add_f32_e32 v96, 1.0, v96
	v_rcp_f32_e32 v96, v96
	s_nop 0
	v_mul_f32_e32 v92, v92, v96
	v_mul_f32_e32 v88, v88, v92
	v_mul_f32_e32 v92, 0xbfb8aa3b, v93
	v_exp_f32_e32 v92, v92
	s_nop 0
	v_add_f32_e32 v92, 1.0, v92
	v_rcp_f32_e32 v92, v92
	s_nop 0
	v_mul_f32_e32 v92, v93, v92
	v_mul_f32_e32 v89, v89, v92
	v_mul_f32_e32 v92, 0xbfb8aa3b, v94
	v_exp_f32_e32 v92, v92
	s_nop 0
	v_add_f32_e32 v92, 1.0, v92
	v_rcp_f32_e32 v92, v92
	s_nop 0
	v_mul_f32_e32 v92, v94, v92
	v_mul_f32_e32 v90, v90, v92
	v_mul_f32_e32 v92, 0xbfb8aa3b, v95
	v_exp_f32_e32 v92, v92
	s_nop 0
	v_add_f32_e32 v92, 1.0, v92
	v_rcp_f32_e32 v92, v92
	s_nop 0
	v_mul_f32_e32 v92, v95, v92
	v_mul_f32_e32 v91, v91, v92
	v_mul_f32_e32 v92, 0xbfb8aa3b, v84
	v_exp_f32_e32 v92, v92
	s_nop 0
	v_add_f32_e32 v92, 1.0, v92
	v_rcp_f32_e32 v92, v92
	s_nop 0
	v_mul_f32_e32 v84, v84, v92
	v_mul_f32_e32 v84, v80, v84
	v_mul_f32_e32 v80, 0xbfb8aa3b, v85
	v_exp_f32_e32 v80, v80
	s_nop 0
	v_add_f32_e32 v80, 1.0, v80
	v_rcp_f32_e32 v80, v80
	s_nop 0
	v_mul_f32_e32 v80, v85, v80
	v_mul_f32_e32 v85, v81, v80
	v_mul_f32_e32 v80, 0xbfb8aa3b, v86
	v_exp_f32_e32 v80, v80
	v_cvt_pk_bf16_f32 v81, v90, v91
	s_nop 0
	v_add_f32_e32 v80, 1.0, v80
	v_rcp_f32_e32 v80, v80
	s_nop 0
	v_mul_f32_e32 v80, v86, v80
	v_mul_f32_e32 v86, v82, v80
	v_mul_f32_e32 v80, 0xbfb8aa3b, v87
	v_exp_f32_e32 v80, v80
	v_cvt_pk_bf16_f32 v82, v84, v85
	s_nop 0
	v_add_f32_e32 v80, 1.0, v80
	v_rcp_f32_e32 v80, v80
	s_nop 0
	v_mul_f32_e32 v80, v87, v80
	v_or_b32_e32 v87, 32, v142
	v_mad_i64_i32 v[84:85], s[12:13], v87, s92, v[112:113]
	v_mul_f32_e32 v83, v83, v80
	v_cvt_pk_bf16_f32 v80, v88, v89
	v_lshl_add_u64 v[84:85], v[84:85], 0, v[114:115]
	v_cvt_pk_bf16_f32 v83, v86, v83
	global_store_dwordx4 v[84:85], v[80:83], off nt
	s_nop 1
	v_mul_f32_e32 v80, 0xbfb8aa3b, v76
	v_exp_f32_e32 v80, v80
	s_nop 0
	v_add_f32_e32 v80, 1.0, v80
	v_rcp_f32_e32 v80, v80
	s_nop 0
	v_mul_f32_e32 v76, v76, v80
	v_mul_f32_e32 v72, v72, v76
	v_mul_f32_e32 v76, 0xbfb8aa3b, v77
	v_exp_f32_e32 v76, v76
	s_nop 0
	v_add_f32_e32 v76, 1.0, v76
	v_rcp_f32_e32 v76, v76
	s_nop 0
	v_mul_f32_e32 v76, v77, v76
	v_mul_f32_e32 v73, v73, v76
	v_mul_f32_e32 v76, 0xbfb8aa3b, v78
	v_exp_f32_e32 v76, v76
	s_nop 0
	v_add_f32_e32 v76, 1.0, v76
	v_rcp_f32_e32 v76, v76
	s_nop 0
	v_mul_f32_e32 v76, v78, v76
	v_mul_f32_e32 v74, v74, v76
	v_mul_f32_e32 v76, 0xbfb8aa3b, v79
	v_exp_f32_e32 v76, v76
	s_nop 0
	v_add_f32_e32 v76, 1.0, v76
	v_rcp_f32_e32 v76, v76
	s_nop 0
	v_mul_f32_e32 v76, v79, v76
	v_mul_f32_e32 v75, v75, v76
	v_mul_f32_e32 v76, 0xbfb8aa3b, v68
	v_exp_f32_e32 v76, v76
	s_nop 0
	v_add_f32_e32 v76, 1.0, v76
	v_rcp_f32_e32 v76, v76
	s_nop 0
	v_mul_f32_e32 v68, v68, v76
	v_mul_f32_e32 v68, v64, v68
	v_mul_f32_e32 v64, 0xbfb8aa3b, v69
	v_exp_f32_e32 v64, v64
	s_nop 0
	v_add_f32_e32 v64, 1.0, v64
	v_rcp_f32_e32 v64, v64
	s_nop 0
	v_mul_f32_e32 v64, v69, v64
	v_mul_f32_e32 v69, v65, v64
	v_mul_f32_e32 v64, 0xbfb8aa3b, v70
	v_exp_f32_e32 v64, v64
	v_cvt_pk_bf16_f32 v65, v74, v75
	s_nop 0
	v_add_f32_e32 v64, 1.0, v64
	v_rcp_f32_e32 v64, v64
	s_nop 0
	v_mul_f32_e32 v64, v70, v64
	v_mul_f32_e32 v70, v66, v64
	v_mul_f32_e32 v64, 0xbfb8aa3b, v71
	v_exp_f32_e32 v64, v64
	v_cvt_pk_bf16_f32 v66, v68, v69
	s_nop 0
	v_add_f32_e32 v64, 1.0, v64
	v_rcp_f32_e32 v64, v64
	s_nop 0
	v_mul_f32_e32 v64, v71, v64
	v_or_b32_e32 v71, 48, v142
	v_mad_i64_i32 v[68:69], s[12:13], v71, s92, v[112:113]
	v_mul_f32_e32 v67, v67, v64
	v_lshl_add_u64 v[68:69], v[68:69], 0, v[114:115]
	v_cvt_pk_bf16_f32 v64, v72, v73
	v_cvt_pk_bf16_f32 v67, v70, v67
	global_store_dwordx4 v[68:69], v[64:67], off nt
	s_nop 1
	v_mul_f32_e32 v65, 0xbfb8aa3b, v60
	v_exp_f32_e32 v65, v65
	v_add_u32_e32 v64, 0x80, v142
	v_add_f32_e32 v65, 1.0, v65
	v_rcp_f32_e32 v65, v65
	s_nop 0
	v_mul_f32_e32 v60, v60, v65
	v_mul_f32_e32 v56, v56, v60
	v_mul_f32_e32 v60, 0xbfb8aa3b, v61
	v_exp_f32_e32 v60, v60
	s_nop 0
	v_add_f32_e32 v60, 1.0, v60
	v_rcp_f32_e32 v60, v60
	s_nop 0
	v_mul_f32_e32 v60, v61, v60
	v_mul_f32_e32 v57, v57, v60
	v_mul_f32_e32 v60, 0xbfb8aa3b, v62
	v_exp_f32_e32 v60, v60
	s_nop 0
	v_add_f32_e32 v60, 1.0, v60
	v_rcp_f32_e32 v60, v60
	s_nop 0
	v_mul_f32_e32 v60, v62, v60
	v_mul_f32_e32 v58, v58, v60
	v_mul_f32_e32 v60, 0xbfb8aa3b, v63
	v_exp_f32_e32 v60, v60
	s_nop 0
	v_add_f32_e32 v60, 1.0, v60
	v_rcp_f32_e32 v60, v60
	s_nop 0
	v_mul_f32_e32 v60, v63, v60
	v_mul_f32_e32 v59, v59, v60
	v_mul_f32_e32 v60, 0xbfb8aa3b, v52
	v_exp_f32_e32 v60, v60
	s_nop 0
	v_add_f32_e32 v60, 1.0, v60
	v_rcp_f32_e32 v60, v60
	s_nop 0
	v_mul_f32_e32 v52, v52, v60
	v_mul_f32_e32 v52, v48, v52
	v_mul_f32_e32 v48, 0xbfb8aa3b, v53
	v_exp_f32_e32 v48, v48
	s_nop 0
	v_add_f32_e32 v48, 1.0, v48
	v_rcp_f32_e32 v48, v48
	s_nop 0
	v_mul_f32_e32 v48, v53, v48
	v_mul_f32_e32 v53, v49, v48
	v_mul_f32_e32 v48, 0xbfb8aa3b, v54
	v_exp_f32_e32 v48, v48
	v_cvt_pk_bf16_f32 v49, v58, v59
	s_nop 0
	v_add_f32_e32 v48, 1.0, v48
	v_rcp_f32_e32 v48, v48
	s_nop 0
	v_mul_f32_e32 v48, v54, v48
	v_mul_f32_e32 v54, v50, v48
	v_mul_f32_e32 v48, 0xbfb8aa3b, v55
	v_exp_f32_e32 v48, v48
	v_cvt_pk_bf16_f32 v50, v52, v53
	v_mad_i64_i32 v[52:53], s[12:13], v64, s92, v[112:113]
	v_add_f32_e32 v48, 1.0, v48
	v_rcp_f32_e32 v48, v48
	v_lshl_add_u64 v[52:53], v[52:53], 0, v[114:115]
	v_mul_f32_e32 v48, v55, v48
	v_mul_f32_e32 v51, v51, v48
	v_cvt_pk_bf16_f32 v48, v56, v57
	v_cvt_pk_bf16_f32 v51, v54, v51
	global_store_dwordx4 v[52:53], v[48:51], off nt
	s_nop 1
	v_mul_f32_e32 v48, 0xbfb8aa3b, v44
	v_exp_f32_e32 v48, v48
	s_nop 0
	v_add_f32_e32 v48, 1.0, v48
	v_rcp_f32_e32 v48, v48
	s_nop 0
	v_mul_f32_e32 v44, v44, v48
	v_mul_f32_e32 v40, v40, v44
	v_mul_f32_e32 v44, 0xbfb8aa3b, v45
	v_exp_f32_e32 v44, v44
	s_nop 0
	v_add_f32_e32 v44, 1.0, v44
	v_rcp_f32_e32 v44, v44
	s_nop 0
	v_mul_f32_e32 v44, v45, v44
	v_mul_f32_e32 v41, v41, v44
	v_mul_f32_e32 v44, 0xbfb8aa3b, v46
	v_exp_f32_e32 v44, v44
	s_nop 0
	v_add_f32_e32 v44, 1.0, v44
	v_rcp_f32_e32 v44, v44
	s_nop 0
	v_mul_f32_e32 v44, v46, v44
	v_mul_f32_e32 v42, v42, v44
	v_mul_f32_e32 v44, 0xbfb8aa3b, v47
	v_exp_f32_e32 v44, v44
	s_nop 0
	v_add_f32_e32 v44, 1.0, v44
	v_rcp_f32_e32 v44, v44
	s_nop 0
	v_mul_f32_e32 v44, v47, v44
	v_mul_f32_e32 v43, v43, v44
	v_mul_f32_e32 v44, 0xbfb8aa3b, v36
	v_exp_f32_e32 v44, v44
	s_nop 0
	v_add_f32_e32 v44, 1.0, v44
	v_rcp_f32_e32 v44, v44
	s_nop 0
	v_mul_f32_e32 v36, v36, v44
	v_mul_f32_e32 v36, v32, v36
	v_mul_f32_e32 v32, 0xbfb8aa3b, v37
	v_exp_f32_e32 v32, v32
	s_nop 0
	v_add_f32_e32 v32, 1.0, v32
	v_rcp_f32_e32 v32, v32
	s_nop 0
	v_mul_f32_e32 v32, v37, v32
	v_mul_f32_e32 v37, v33, v32
	v_mul_f32_e32 v32, 0xbfb8aa3b, v38
	v_exp_f32_e32 v32, v32
	v_cvt_pk_bf16_f32 v33, v42, v43
	s_nop 0
	v_add_f32_e32 v32, 1.0, v32
	v_rcp_f32_e32 v32, v32
	s_nop 0
	v_mul_f32_e32 v32, v38, v32
	v_mul_f32_e32 v38, v34, v32
	v_mul_f32_e32 v32, 0xbfb8aa3b, v39
	v_exp_f32_e32 v32, v32
	v_cvt_pk_bf16_f32 v34, v36, v37
	s_nop 0
	v_add_f32_e32 v32, 1.0, v32
	v_rcp_f32_e32 v32, v32
	s_nop 0
	v_mul_f32_e32 v32, v39, v32
	v_add_u32_e32 v39, 0x90, v142
	v_mad_i64_i32 v[36:37], s[12:13], v39, s92, v[112:113]
	v_mul_f32_e32 v35, v35, v32
	v_cvt_pk_bf16_f32 v32, v40, v41
	v_lshl_add_u64 v[36:37], v[36:37], 0, v[114:115]
	v_cvt_pk_bf16_f32 v35, v38, v35
	global_store_dwordx4 v[36:37], v[32:35], off nt
	s_nop 1
	v_mul_f32_e32 v32, 0xbfb8aa3b, v28
	v_exp_f32_e32 v32, v32
	s_nop 0
	v_add_f32_e32 v32, 1.0, v32
	v_rcp_f32_e32 v32, v32
	s_nop 0
	v_mul_f32_e32 v28, v28, v32
	v_mul_f32_e32 v24, v24, v28
	v_mul_f32_e32 v28, 0xbfb8aa3b, v29
	v_exp_f32_e32 v28, v28
	s_nop 0
	v_add_f32_e32 v28, 1.0, v28
	v_rcp_f32_e32 v28, v28
	s_nop 0
	v_mul_f32_e32 v28, v29, v28
	v_mul_f32_e32 v25, v25, v28
	v_mul_f32_e32 v28, 0xbfb8aa3b, v30
	v_exp_f32_e32 v28, v28
	s_nop 0
	v_add_f32_e32 v28, 1.0, v28
	v_rcp_f32_e32 v28, v28
	s_nop 0
	v_mul_f32_e32 v28, v30, v28
	v_mul_f32_e32 v26, v26, v28
	v_mul_f32_e32 v28, 0xbfb8aa3b, v31
	v_exp_f32_e32 v28, v28
	s_nop 0
	v_add_f32_e32 v28, 1.0, v28
	v_rcp_f32_e32 v28, v28
	s_nop 0
	v_mul_f32_e32 v28, v31, v28
	v_mul_f32_e32 v27, v27, v28
	v_mul_f32_e32 v28, 0xbfb8aa3b, v20
	v_exp_f32_e32 v28, v28
	s_nop 0
	v_add_f32_e32 v28, 1.0, v28
	v_rcp_f32_e32 v28, v28
	s_nop 0
	v_mul_f32_e32 v20, v20, v28
	v_mul_f32_e32 v20, v16, v20
	v_mul_f32_e32 v16, 0xbfb8aa3b, v21
	v_exp_f32_e32 v16, v16
	s_nop 0
	v_add_f32_e32 v16, 1.0, v16
	v_rcp_f32_e32 v16, v16
	s_nop 0
	v_mul_f32_e32 v16, v21, v16
	v_mul_f32_e32 v21, v17, v16
	v_mul_f32_e32 v16, 0xbfb8aa3b, v22
	v_exp_f32_e32 v16, v16
	v_cvt_pk_bf16_f32 v17, v26, v27
	s_nop 0
	v_add_f32_e32 v16, 1.0, v16
	v_rcp_f32_e32 v16, v16
	s_nop 0
	v_mul_f32_e32 v16, v22, v16
	v_mul_f32_e32 v22, v18, v16
	v_mul_f32_e32 v16, 0xbfb8aa3b, v23
	v_exp_f32_e32 v16, v16
	v_cvt_pk_bf16_f32 v18, v20, v21
	s_nop 0
	v_add_f32_e32 v16, 1.0, v16
	v_rcp_f32_e32 v16, v16
	s_nop 0
	v_mul_f32_e32 v16, v23, v16
	v_add_u32_e32 v23, 0xa0, v142
	v_mad_i64_i32 v[20:21], s[12:13], v23, s92, v[112:113]
	v_mul_f32_e32 v19, v19, v16
	v_cvt_pk_bf16_f32 v16, v24, v25
	v_lshl_add_u64 v[20:21], v[20:21], 0, v[114:115]
	v_cvt_pk_bf16_f32 v19, v22, v19
	global_store_dwordx4 v[20:21], v[16:19], off nt
	s_nop 1
	v_mul_f32_e32 v16, 0xbfb8aa3b, v12
	v_exp_f32_e32 v16, v16
	s_nop 0
	v_add_f32_e32 v16, 1.0, v16
	v_rcp_f32_e32 v16, v16
	s_nop 0
	v_mul_f32_e32 v12, v12, v16
	v_mul_f32_e32 v8, v8, v12
	v_mul_f32_e32 v12, 0xbfb8aa3b, v13
	v_exp_f32_e32 v12, v12
	s_nop 0
	v_add_f32_e32 v12, 1.0, v12
	v_rcp_f32_e32 v12, v12
	s_nop 0
	v_mul_f32_e32 v12, v13, v12
	v_mul_f32_e32 v9, v9, v12
	v_mul_f32_e32 v12, 0xbfb8aa3b, v14
	v_exp_f32_e32 v12, v12
	s_nop 0
	v_add_f32_e32 v12, 1.0, v12
	v_rcp_f32_e32 v12, v12
	s_nop 0
	v_mul_f32_e32 v12, v14, v12
	v_mul_f32_e32 v10, v10, v12
	v_mul_f32_e32 v12, 0xbfb8aa3b, v15
	v_exp_f32_e32 v12, v12
	s_nop 0
	v_add_f32_e32 v12, 1.0, v12
	v_rcp_f32_e32 v12, v12
	s_nop 0
	v_mul_f32_e32 v12, v15, v12
	v_mul_f32_e32 v11, v11, v12
	v_mul_f32_e32 v12, 0xbfb8aa3b, v4
	v_exp_f32_e32 v12, v12
	s_nop 0
	v_add_f32_e32 v12, 1.0, v12
	v_rcp_f32_e32 v12, v12
	s_nop 0
	v_mul_f32_e32 v4, v4, v12
	v_mul_f32_e32 v4, v0, v4
	v_mul_f32_e32 v0, 0xbfb8aa3b, v5
	v_exp_f32_e32 v0, v0
	s_nop 0
	v_add_f32_e32 v0, 1.0, v0
	v_rcp_f32_e32 v0, v0
	s_nop 0
	v_mul_f32_e32 v0, v5, v0
	v_mul_f32_e32 v5, v1, v0
	v_mul_f32_e32 v0, 0xbfb8aa3b, v6
	v_exp_f32_e32 v0, v0
	v_cvt_pk_bf16_f32 v1, v10, v11
	s_nop 0
	v_add_f32_e32 v0, 1.0, v0
	v_rcp_f32_e32 v0, v0
	s_nop 0
	v_mul_f32_e32 v0, v6, v0
	v_mul_f32_e32 v6, v2, v0
	v_mul_f32_e32 v0, 0xbfb8aa3b, v7
	v_exp_f32_e32 v0, v0
	v_cvt_pk_bf16_f32 v2, v4, v5
	s_nop 0
	v_add_f32_e32 v0, 1.0, v0
	v_rcp_f32_e32 v0, v0
	s_nop 0
	v_mul_f32_e32 v0, v7, v0
	v_add_u32_e32 v7, 0xb0, v142
	v_mad_i64_i32 v[4:5], s[12:13], v7, s92, v[112:113]
	v_mul_f32_e32 v3, v3, v0
	v_lshl_add_u64 v[4:5], v[4:5], 0, v[114:115]
	v_cvt_pk_bf16_f32 v0, v8, v9
	v_cvt_pk_bf16_f32 v3, v6, v3
	global_store_dwordx4 v[4:5], v[0:3], off nt
	s_cbranch_vccnz .LBB0_130
	s_andn2_b64 vcc, exec, s[46:47]
	s_cbranch_vccnz .LBB0_129
	s_barrier
	s_branch .LBB0_129
